# v29: v26 with the attention KV loop shifted by +4 bytes (code-placement / byte-phase test, loop head from 4 mod 8 to 0 mod 8)
# baseline (speedup 1.0000x reference)
.LBB0_525:
	s_mul_i32 s7, s7, 0x9800
	s_mul_hi_u32 s8, s6, 0x9800
	s_and_b32 s4, s10, 15
	s_add_i32 s8, s8, s7
	s_mul_i32 s6, s6, 0x9800
	s_add_u32 s6, s50, s6
	s_addc_u32 s7, s51, s8
	s_lshl_b32 s4, s4, 8
	s_add_u32 s48, s6, s4
	s_addc_u32 s49, s7, 0
	s_lshl_b32 s4, s11, 2
	s_bfe_u32 s6, s10, 0x20002
	s_or_b32 s26, s4, s6
	v_mbcnt_lo_u32_b32 v76, -1, 0
	v_mbcnt_hi_u32_b32 v76, -1, v76
	s_mul_i32 s6, s26, 0x210000
	v_add_u32_e32 v54, s39, v76
	v_ashrrev_i32_e32 v16, 4, v54
	s_mul_hi_i32 s4, s26, 0x210000
	s_add_u32 s40, s52, s6
	v_lshlrev_b32_e32 v22, 3, v76
	v_add_u32_e32 v18, 32, v16
	s_addc_u32 s41, s53, s4
	v_and_b32_e32 v0, 0x78, v22
	v_ashrrev_i32_e32 v17, 31, v16
	v_ashrrev_i32_e32 v19, 31, v18
	s_add_u32 s42, s54, s6
	v_lshlrev_b32_e32 v23, 1, v0
	v_lshlrev_b64 v[48:49], 8, v[16:17]
	v_lshlrev_b64 v[8:9], 8, v[18:19]
	s_addc_u32 s43, s55, s4
	v_or_b32_e32 v52, v48, v23
	v_mov_b32_e32 v53, v49
	v_or_b32_e32 v8, v8, v23
	v_lshl_add_u64 v[0:1], s[42:43], 0, v[52:53]
	v_lshl_add_u64 v[4:5], s[42:43], 0, v[8:9]
	v_lshl_add_u64 v[10:11], s[40:41], 0, v[52:53]
	v_lshl_add_u64 v[12:13], s[40:41], 0, v[8:9]
	global_load_dwordx4 v[0:3], v[0:1], off
	s_nop 0
	global_load_dwordx4 v[4:7], v[4:5], off
	s_nop 0
	global_load_dwordx4 v[8:11], v[10:11], off
	s_nop 0
	global_load_dwordx4 v[12:15], v[12:13], off
	v_ashrrev_i32_e32 v55, 1, v54
	s_movk_i32 s4, 0xffe0
	v_bfe_u32 v97, v76, 5, 1
	v_bfi_b32 v17, s4, v55, v76
	v_mov_b64_e32 v[20:21], s[48:49]
	v_mad_i64_i32 v[20:21], s[6:7], v17, s21, v[20:21]
	v_lshlrev_b32_e32 v50, 4, v97
	v_mov_b32_e32 v51, v96
	v_lshl_add_u64 v[20:21], v[20:21], 0, v[50:51]
	global_load_dwordx4 v[118:121], v[20:21], off
	global_load_dwordx4 v[114:117], v[20:21], off offset:32
	global_load_dwordx4 v[126:129], v[20:21], off offset:64
	global_load_dwordx4 v[122:125], v[20:21], off offset:96
	global_load_dwordx4 v[110:113], v[20:21], off offset:128
	global_load_dwordx4 v[106:109], v[20:21], off offset:160
	global_load_dwordx4 v[102:105], v[20:21], off offset:192
	global_load_dwordx4 v[98:101], v[20:21], off offset:224
	v_bfe_u32 v17, v22, 5, 2
	v_and_b32_e32 v22, 0xfffff0, v16
	v_lshlrev_b32_e32 v24, 1, v16
	v_lshrrev_b32_e32 v25, 1, v16
	v_and_b32_e32 v26, 3, v16
	v_and_b32_e32 v19, 0xf0, v54
	v_lshlrev_b32_e32 v16, 8, v16
	v_and_or_b32 v22, v24, 8, v22
	v_bfe_u32 v24, v24, 1, 3
	v_and_b32_e32 v26, 0xfffff0, v18
	v_lshlrev_b32_e32 v27, 1, v18
	v_bitop3_b32 v16, v23, v16, v19 bitop3:0xde
	v_lshlrev_b32_e32 v18, 8, v18
	v_and_b32_e32 v22, 12, v25
	v_and_or_b32 v26, v27, 8, v26
	v_add_u32_e32 v188, 0, v16
	v_bitop3_b32 v16, v18, v23, v19 bitop3:0xf6
	v_or_b32_e32 v18, v22, v17
	v_and_or_b32 v19, v25, 12, 16
	v_and_b32_e32 v25, 48, v23
	v_lshlrev_b32_e32 v24, 6, v24
	v_add_u32_e32 v189, 0, v16
	v_lshlrev_b32_e32 v16, 9, v18
	v_or_b32_e32 v17, v19, v17
	v_or3_b32 v16, v16, v24, v25
	v_lshlrev_b32_e32 v17, 9, v17
	v_and_b32_e32 v180, 31, v76
	v_lshlrev_b32_e32 v51, 4, v76
	v_or3_b32 v17, v17, v24, v25
	v_add_u32_e32 v190, 0, v16
	v_add_u32_e32 v191, 0, v17
	s_waitcnt vmcnt(0)
	s_add_i32 s4, 0, 0x10000
	s_mov_b64 s[6:7], 0x6000
	v_and_b32_e32 v181, 0xffffffe0, v55
	v_and_b32_e32 v77, 63, v76
	s_mov_b32 s8, s5
	s_mov_b32 s9, s5
	s_mov_b32 s10, s5
	s_mov_b32 s11, s5
	s_mov_b32 s12, s5
	s_waitcnt vmcnt(0)
	ds_write_b128 v190, v[0:3]
	s_waitcnt vmcnt(10)
	ds_write_b128 v191, v[4:7]
	s_waitcnt vmcnt(9)
	ds_write_b128 v188, v[8:11] offset:32768
	s_waitcnt vmcnt(8)
	ds_write_b128 v189, v[12:15] offset:32768
	v_lshlrev_b32_e32 v12, 8, v180
	v_and_b32_e32 v13, 0xf0, v51
	v_bitop3_b32 v0, v50, v12, v13 bitop3:0xde
	v_add_u32_e32 v192, 0, v0
	s_waitcnt lgkmcnt(0)
	s_barrier
	ds_read_b128 v[0:3], v192 offset:32768
	ds_read_b128 v[4:7], v192 offset:40960
	s_waitcnt vmcnt(7) lgkmcnt(1)
	v_mfma_f32_32x32x16_bf16 v[16:31], v[0:3], v[118:121], 0
	v_or_b32_e32 v0, 32, v50
	v_bitop3_b32 v0, v0, v12, v13 bitop3:0xde
	v_add_u32_e32 v200, 0, v0
	v_lshl_add_u64 v[8:9], v[52:53], 0, s[6:7]
	v_lshl_add_u64 v[10:11], s[42:43], 0, v[8:9]
	v_lshlrev_b32_e32 v14, 3, v77
	v_and_b32_e32 v15, 0xc0, v51
	s_waitcnt lgkmcnt(0)
	v_mfma_f32_32x32x16_bf16 v[32:47], v[4:7], v[118:121], 0
	ds_read_b128 v[0:3], v200 offset:32768
	ds_read_b128 v[4:7], v200 offset:40960
	s_mov_b32 s6, s5
	s_mov_b32 s7, s5
	s_mov_b32 s13, s5
	s_mov_b32 s14, s5
	s_mov_b32 s15, s5
	s_mov_b32 s16, s5
	s_waitcnt vmcnt(6) lgkmcnt(1)
	v_mfma_f32_32x32x16_bf16 v[16:31], v[0:3], v[114:117], v[16:31]
	v_or_b32_e32 v0, 64, v50
	v_bitop3_b32 v0, v0, v12, v13 bitop3:0xde
	v_add_u32_e32 v199, 0, v0
	s_mov_b32 s17, s5
	s_mov_b32 s18, s5
	s_mov_b32 s19, s5
	s_cmp_lg_u32 0, -1
	s_waitcnt lgkmcnt(0)
	v_mfma_f32_32x32x16_bf16 v[32:47], v[4:7], v[114:117], v[32:47]
	ds_read_b128 v[0:3], v199 offset:32768
	ds_read_b128 v[4:7], v199 offset:40960
	s_cselect_b32 s27, 0, 0
	v_lshlrev_b32_e32 v183, 2, v97
	v_mov_b32_e32 v185, 0
	s_waitcnt vmcnt(5) lgkmcnt(1)
	v_mfma_f32_32x32x16_bf16 v[16:31], v[0:3], v[126:129], v[16:31]
	v_or_b32_e32 v0, 0x60, v50
	v_bitop3_b32 v0, v0, v12, v13 bitop3:0xde
	v_add_u32_e32 v198, 0, v0
	s_waitcnt lgkmcnt(0)
	v_mfma_f32_32x32x16_bf16 v[32:47], v[4:7], v[126:129], v[32:47]
	ds_read_b128 v[0:3], v198 offset:32768
	ds_read_b128 v[4:7], v198 offset:40960
	s_waitcnt vmcnt(4) lgkmcnt(1)
	v_mfma_f32_32x32x16_bf16 v[16:31], v[0:3], v[122:125], v[16:31]
	v_or_b32_e32 v0, 0x80, v50
	v_bitop3_b32 v0, v0, v12, v13 bitop3:0xde
	v_add_u32_e32 v195, 0, v0
	s_waitcnt lgkmcnt(0)
	v_mfma_f32_32x32x16_bf16 v[32:47], v[4:7], v[122:125], v[32:47]
	ds_read_b128 v[0:3], v195 offset:32768
	ds_read_b128 v[4:7], v195 offset:40960
	s_waitcnt vmcnt(3) lgkmcnt(1)
	v_mfma_f32_32x32x16_bf16 v[16:31], v[0:3], v[110:113], v[16:31]
	v_or_b32_e32 v0, 0xa0, v50
	v_bitop3_b32 v0, v0, v12, v13 bitop3:0xde
	v_add_u32_e32 v193, 0, v0
	ds_read_b128 v[0:3], v193 offset:32768
	s_waitcnt lgkmcnt(1)
	v_mfma_f32_32x32x16_bf16 v[32:47], v[4:7], v[110:113], v[32:47]
	v_and_b32_e32 v4, 0x3fffffc0, v54
	v_lshl_add_u32 v78, v4, 2, s4
	ds_read_b128 v[4:7], v193 offset:40960
	s_mov_b32 s4, s5
	v_add_u32_e32 v182, v78, v50
	v_lshl_add_u32 v184, v180, 2, v78
	s_waitcnt vmcnt(2) lgkmcnt(1)
	v_mfma_f32_32x32x16_bf16 v[16:31], v[0:3], v[106:109], v[16:31]
	v_lshl_add_u64 v[0:1], v[52:53], 0, s[68:69]
	v_lshl_add_u64 v[2:3], s[42:43], 0, v[0:1]
	v_lshl_add_u64 v[0:1], s[40:41], 0, v[0:1]
	global_load_dwordx4 v[54:57], v[2:3], off
	global_load_dwordx4 v[58:61], v[10:11], off
	v_lshl_add_u64 v[2:3], s[40:41], 0, v[8:9]
	global_load_dwordx4 v[62:65], v[0:1], off
	global_load_dwordx4 v[66:69], v[2:3], off
	v_or_b32_e32 v0, 0xc0, v50
	v_bitop3_b32 v0, v0, v12, v13 bitop3:0xde
	v_add_u32_e32 v202, 0, v0
	ds_read_b128 v[0:3], v202 offset:32768
	v_lshlrev_b32_e32 v9, 1, v76
	v_and_or_b32 v8, v14, 24, v15
	s_waitcnt lgkmcnt(1)
	v_mfma_f32_32x32x16_bf16 v[32:47], v[4:7], v[106:109], v[32:47]
	v_and_b32_e32 v4, 32, v9
	v_and_b32_e32 v5, 0x100, v14
	v_or3_b32 v51, v8, v4, v5
	ds_read_b128 v[4:7], v202 offset:40960
	v_add_u32_e32 v187, s27, v51
	s_waitcnt vmcnt(5) lgkmcnt(1)
	v_mfma_f32_32x32x16_bf16 v[16:31], v[0:3], v[102:105], v[16:31]
	v_or_b32_e32 v0, 0xe0, v50
	v_bitop3_b32 v0, v0, v12, v13 bitop3:0xde
	v_add_u32_e32 v201, 0, v0
	ds_read_b128 v[0:3], v201 offset:32768
	ds_read_b128 v[70:73], v201 offset:40960
	s_waitcnt lgkmcnt(2)
	v_mfma_f32_32x32x16_bf16 v[32:47], v[4:7], v[102:105], v[32:47]
	s_waitcnt vmcnt(4) lgkmcnt(1)
	v_mfma_f32_32x32x16_bf16 v[16:31], v[0:3], v[98:101], v[16:31]
	v_mov_b64_e32 v[0:1], s[4:5]
	v_mov_b64_e32 v[2:3], s[6:7]
	v_mov_b64_e32 v[4:5], s[8:9]
	v_mov_b64_e32 v[6:7], s[10:11]
	v_mov_b64_e32 v[8:9], s[12:13]
	v_mov_b64_e32 v[10:11], s[14:15]
	v_mov_b64_e32 v[12:13], s[16:17]
	s_waitcnt lgkmcnt(0)
	v_mfma_f32_32x32x16_bf16 v[32:47], v[70:73], v[98:101], v[32:47]
	s_nop 2
	v_max_f32_e32 v70, v17, v17
	v_max_f32_e32 v71, v16, v16
	v_max_f32_e32 v70, v71, v70
	v_max3_f32 v70, v70, v18, v19
	v_max3_f32 v70, v70, v20, v21
	v_max3_f32 v70, v70, v22, v23
	v_max3_f32 v70, v70, v24, v25
	v_max3_f32 v70, v70, v26, v27
	v_max3_f32 v70, v70, v28, v29
	v_max3_f32 v70, v70, v30, v31
	v_max3_f32 v70, v70, v32, v33
	v_max3_f32 v70, v70, v34, v35
	v_max3_f32 v70, v70, v36, v37
	v_max3_f32 v70, v70, v38, v39
	v_max3_f32 v70, v70, v40, v41
	v_max3_f32 v70, v70, v42, v43
	v_mov_b64_e32 v[14:15], s[18:19]
	v_max3_f32 v70, v70, v44, v45
	s_mov_b64 s[6:7], 0x8000
	v_max3_f32 v79, v70, v46, v47
	v_lshl_add_u64 v[70:71], v[52:53], 0, s[6:7]
	s_mov_b64 s[6:7], 0xa000
	v_lshl_add_u64 v[72:73], s[42:43], 0, v[70:71]
	v_lshl_add_u64 v[52:53], v[52:53], 0, s[6:7]
	v_lshl_add_u64 v[70:71], s[40:41], 0, v[70:71]
	v_lshl_add_u64 v[74:75], s[42:43], 0, v[52:53]
	global_load_dwordx4 v[130:133], v[72:73], off
	global_load_dwordx4 v[138:141], v[74:75], off
	v_lshl_add_u64 v[52:53], s[40:41], 0, v[52:53]
	global_load_dwordx4 v[134:137], v[70:71], off
	global_load_dwordx4 v[142:145], v[52:53], off
	v_mov_b32_e32 v80, v79
	s_nop 1
	v_permlane32_swap_b32_e32 v79, v80
	v_max_f32_e32 v52, v80, v80
	v_max_f32_e32 v53, v79, v79
	v_max_f32_e32 v52, v53, v52
	v_add_f32_e32 v53, 0x7149f2ca, v52
	v_max_f32_e32 v52, 0xf149f2ca, v52
	v_cmp_ge_f32_e32 vcc, s92, v53
	v_sub_f32_e32 v53, 0xf149f2ca, v52
	v_mul_f32_e32 v53, 0x3e0293ee, v53
	v_exp_f32_e32 v53, v53
	s_cmp_eq_u64 vcc, exec
	s_cselect_b64 vcc, -1, 0
	s_waitcnt vmcnt(4)
	v_cndmask_b32_e64 v203, v53, 1.0, vcc
	v_mov_b32_e32 v53, 0xf149f2ca
	v_cndmask_b32_e32 v170, v52, v53, vcc
	v_mul_f32_e32 v52, 0xbe0293ee, v170
	v_fmamk_f32 v16, v16, 0x3e0293ee, v52
	v_exp_f32_e32 v163, v16
	v_fmamk_f32 v16, v17, 0x3e0293ee, v52
	v_exp_f32_e32 v177, v16
	v_fmamk_f32 v16, v18, 0x3e0293ee, v52
	v_exp_f32_e32 v164, v16
	v_fmamk_f32 v16, v19, 0x3e0293ee, v52
	v_exp_f32_e32 v207, v16
	v_fmamk_f32 v16, v20, 0x3e0293ee, v52
	v_exp_f32_e32 v176, v16
	v_fmamk_f32 v16, v21, 0x3e0293ee, v52
	v_exp_f32_e32 v210, v16
	v_fmamk_f32 v16, v22, 0x3e0293ee, v52
	v_exp_f32_e32 v165, v16
	v_fmamk_f32 v16, v23, 0x3e0293ee, v52
	v_exp_f32_e32 v175, v16
	v_fmamk_f32 v16, v24, 0x3e0293ee, v52
	v_exp_f32_e32 v166, v16
	v_fmamk_f32 v16, v25, 0x3e0293ee, v52
	v_exp_f32_e32 v173, v16
	v_fmamk_f32 v16, v26, 0x3e0293ee, v52
	v_exp_f32_e32 v167, v16
	v_fmamk_f32 v16, v27, 0x3e0293ee, v52
	v_exp_f32_e32 v174, v16
	v_fmamk_f32 v16, v28, 0x3e0293ee, v52
	v_exp_f32_e32 v168, v16
	v_fmamk_f32 v16, v29, 0x3e0293ee, v52
	v_exp_f32_e32 v171, v16
	v_fmamk_f32 v16, v30, 0x3e0293ee, v52
	v_pk_fma_f32 v[146:147], v[46:47], s[88:89], v[52:53] op_sel_hi:[1,0,0]
	v_pk_fma_f32 v[152:153], v[44:45], s[88:89], v[52:53] op_sel_hi:[1,0,0]
	v_pk_fma_f32 v[156:157], v[42:43], s[88:89], v[52:53] op_sel_hi:[1,0,0]
	v_pk_fma_f32 v[148:149], v[40:41], s[88:89], v[52:53] op_sel_hi:[1,0,0]
	v_pk_fma_f32 v[150:151], v[38:39], s[88:89], v[52:53] op_sel_hi:[1,0,0]
	v_pk_fma_f32 v[154:155], v[36:37], s[88:89], v[52:53] op_sel_hi:[1,0,0]
	v_pk_fma_f32 v[158:159], v[34:35], s[88:89], v[52:53] op_sel_hi:[1,0,0]
	v_pk_fma_f32 v[160:161], v[32:33], s[88:89], v[52:53] op_sel_hi:[1,0,0]
	v_exp_f32_e32 v169, v16
	v_fmac_f32_e32 v52, 0x3e0293ee, v31
	v_mov_b32_e32 v16, 0x210000
	v_exp_f32_e32 v172, v52
	v_mad_i64_i32 v[16:17], s[6:7], s26, v16, v[48:49]
	v_and_b32_e32 v18, 15, v76
	s_addk_i32 s27, 0x4000
	v_lshl_or_b32 v16, v18, 4, v16
	s_waitcnt vmcnt(7)
	ds_write_b128 v190, v[54:57] offset:16384
	s_waitcnt vmcnt(6)
	ds_write_b128 v191, v[58:61] offset:16384
	s_waitcnt vmcnt(5)
	ds_write_b128 v188, v[62:65] offset:49152
	s_waitcnt vmcnt(4)
	ds_write_b128 v189, v[66:69] offset:49152
	v_add_u32_e32 v186, s27, v51
	v_lshl_add_u64 v[178:179], s[46:47], 0, v[16:17]
	v_mov_b64_e32 v[62:63], v[14:15]
	v_mov_b64_e32 v[46:47], v[14:15]
	v_mov_b64_e32 v[30:31], v[14:15]
	v_cmp_gt_u32_e64 s[40:41], 32, v77
	v_mov_b64_e32 v[60:61], v[12:13]
	v_mov_b64_e32 v[58:59], v[10:11]
	v_mov_b64_e32 v[56:57], v[8:9]
	v_mov_b64_e32 v[54:55], v[6:7]
	v_mov_b64_e32 v[52:53], v[4:5]
	v_mov_b64_e32 v[50:51], v[2:3]
	v_mov_b64_e32 v[48:49], v[0:1]
	v_mov_b64_e32 v[44:45], v[12:13]
	v_mov_b64_e32 v[42:43], v[10:11]
	v_mov_b64_e32 v[40:41], v[8:9]
	v_mov_b64_e32 v[38:39], v[6:7]
	v_mov_b64_e32 v[36:37], v[4:5]
	v_mov_b64_e32 v[34:35], v[2:3]
	v_mov_b64_e32 v[32:33], v[0:1]
	v_mov_b64_e32 v[28:29], v[12:13]
	v_mov_b64_e32 v[26:27], v[10:11]
	v_mov_b64_e32 v[24:25], v[8:9]
	v_mov_b64_e32 v[22:23], v[6:7]
	v_mov_b64_e32 v[20:21], v[4:5]
	v_mov_b64_e32 v[18:19], v[2:3]
	v_mov_b64_e32 v[16:17], v[0:1]
	s_waitcnt lgkmcnt(0)
	s_barrier
	v_readfirstlane_b32 s66, v178
	v_readfirstlane_b32 s67, v179
	s_nop 3
	v_subrev_u32_e32 v178, s66, v178
	v_add_u32_e32 v179, 0x2000, v178
	s_add_u32 s98, s66, 0xfef7a000
	s_addc_u32 s99, s67, -1
	s_add_u32 s66, s66, 0xffffa000
	s_addc_u32 s67, s67, -1
	v_mov_b32_e32 v243, v170
	v_mul_f32_e32 v242, 0xbe0293ee, v243
	s_nop 0

.LBB0_538:
	s_nop 0
	v_mov_b32_e32 v170, v243
	ds_read_b128 v[64:67], v192 offset:49152
	ds_read_b128 v[68:71], v192 offset:57344
	s_waitcnt lgkmcnt(1)
	v_mfma_f32_32x32x16_bf16 v[80:95], v[64:67], v[118:121], 0
	s_waitcnt lgkmcnt(0)
	v_mfma_f32_32x32x16_bf16 v[64:79], v[68:71], v[118:121], 0
	ds_read_b128 v[118:121], v200 offset:49152
	ds_read_b128 v[130:133], v200 offset:57344
	s_waitcnt lgkmcnt(1)
	v_mfma_f32_32x32x16_bf16 v[80:95], v[118:121], v[114:117], v[80:95]
	s_waitcnt lgkmcnt(0)
	v_mfma_f32_32x32x16_bf16 v[64:79], v[130:133], v[114:117], v[64:79]
	ds_read_b128 v[114:117], v199 offset:49152
	ds_read_b128 v[118:121], v199 offset:57344
	s_waitcnt lgkmcnt(1)
	v_mfma_f32_32x32x16_bf16 v[80:95], v[114:117], v[126:129], v[80:95]
	s_waitcnt lgkmcnt(0)
	v_mfma_f32_32x32x16_bf16 v[64:79], v[118:121], v[126:129], v[64:79]
	ds_read_b128 v[114:117], v198 offset:49152
	ds_read_b128 v[118:121], v198 offset:57344
	s_waitcnt lgkmcnt(1)
	v_mfma_f32_32x32x16_bf16 v[80:95], v[114:117], v[122:125], v[80:95]
	s_waitcnt lgkmcnt(0)
	v_mfma_f32_32x32x16_bf16 v[64:79], v[118:121], v[122:125], v[64:79]
	ds_read_b128 v[114:117], v195 offset:49152
	ds_read_b128 v[118:121], v195 offset:57344
	v_exp_f32_e32 v122, v146
	v_exp_f32_e32 v123, v147
	s_waitcnt lgkmcnt(1)
	v_mfma_f32_32x32x16_bf16 v[80:95], v[114:117], v[110:113], v[80:95]
	s_waitcnt lgkmcnt(0)
	v_mfma_f32_32x32x16_bf16 v[64:79], v[118:121], v[110:113], v[64:79]
	ds_read_b128 v[110:113], v193 offset:49152
	ds_read_b128 v[114:117], v193 offset:57344
	v_exp_f32_e32 v118, v156
	v_exp_f32_e32 v119, v157
	v_exp_f32_e32 v120, v152
	v_exp_f32_e32 v121, v153
	s_waitcnt lgkmcnt(1)
	v_mfma_f32_32x32x16_bf16 v[80:95], v[110:113], v[106:109], v[80:95]
	s_waitcnt lgkmcnt(0)
	v_mfma_f32_32x32x16_bf16 v[64:79], v[114:117], v[106:109], v[64:79]
	ds_read_b128 v[106:109], v202 offset:49152
	ds_read_b128 v[110:113], v202 offset:57344
	v_exp_f32_e32 v114, v150
	v_exp_f32_e32 v115, v151
	v_exp_f32_e32 v116, v148
	v_exp_f32_e32 v117, v149
	s_waitcnt lgkmcnt(1)
	v_mfma_f32_32x32x16_bf16 v[80:95], v[106:109], v[102:105], v[80:95]
	s_waitcnt lgkmcnt(0)
	v_mfma_f32_32x32x16_bf16 v[64:79], v[110:113], v[102:105], v[64:79]
	ds_read_b128 v[102:105], v201 offset:49152
	ds_read_b128 v[106:109], v201 offset:57344
	v_exp_f32_e32 v110, v158
	v_exp_f32_e32 v111, v159
	v_exp_f32_e32 v112, v154
	v_exp_f32_e32 v113, v155
	s_waitcnt lgkmcnt(1)
	v_mfma_f32_32x32x16_bf16 v[80:95], v[102:105], v[98:101], v[80:95]
	s_waitcnt lgkmcnt(0)
	v_mfma_f32_32x32x16_bf16 v[64:79], v[106:109], v[98:101], v[64:79]
	v_add_f32_e32 v98, 0, v163
	v_add_f32_e32 v98, v177, v98
	v_add_f32_e32 v98, v164, v98
	v_add_f32_e32 v98, v207, v98
	v_add_f32_e32 v98, v176, v98
	v_add_f32_e32 v98, v210, v98
	v_add_f32_e32 v98, v165, v98
	v_add_f32_e32 v98, v175, v98
	v_add_f32_e32 v98, v166, v98
	v_add_f32_e32 v98, v173, v98
	v_add_f32_e32 v98, v167, v98
	v_add_f32_e32 v98, v174, v98
	v_exp_f32_e32 v108, v160
	v_add_f32_e32 v98, v168, v98
	v_exp_f32_e32 v109, v161
	v_add_f32_e32 v98, v171, v98
	v_add_f32_e32 v98, v169, v98
	v_add_f32_e32 v98, v172, v98
	v_add_f32_e32 v98, v108, v98
	v_add_f32_e32 v98, v109, v98
	v_add_f32_e32 v98, v110, v98
	v_add_f32_e32 v98, v111, v98
	v_add_f32_e32 v98, v112, v98
	v_add_f32_e32 v98, v113, v98
	v_add_f32_e32 v98, v114, v98
	v_add_f32_e32 v98, v115, v98
	v_add_f32_e32 v98, v116, v98
	v_add_f32_e32 v98, v117, v98
	v_add_f32_e32 v98, v118, v98
	v_add_f32_e32 v98, v119, v98
	v_add_f32_e32 v98, v120, v98
	v_add_f32_e32 v98, v121, v98
	v_add_f32_e32 v98, v122, v98
	v_add_f32_e32 v98, v123, v98
	v_mov_b32_e32 v99, v98
	v_cvt_pk_bf16_f32 v100, v163, v177
	v_cvt_pk_bf16_f32 v101, v164, v207
	v_cvt_pk_bf16_f32 v102, v176, v210
	v_cvt_pk_bf16_f32 v103, v165, v175
	s_nop 1
	v_permlane32_swap_b32_e32 v98, v99
	v_cvt_pk_bf16_f32 v104, v166, v173
	v_cvt_pk_bf16_f32 v105, v167, v174
	v_cvt_pk_bf16_f32 v106, v168, v171
	v_cvt_pk_bf16_f32 v107, v169, v172
	v_cvt_pk_bf16_f32 v108, v108, v109
	v_cvt_pk_bf16_f32 v109, v110, v111
	v_cvt_pk_bf16_f32 v110, v112, v113
	v_cvt_pk_bf16_f32 v111, v114, v115
	v_cvt_pk_bf16_f32 v112, v116, v117
	v_cvt_pk_bf16_f32 v113, v118, v119
	v_cvt_pk_bf16_f32 v114, v120, v121
	v_cvt_pk_bf16_f32 v115, v122, v123
	s_nop 0
	ds_read_b64_tr_b16 v[116:117], v187 offset:0
	ds_read_b64_tr_b16 v[118:119], v187 offset:0x800
	ds_read_b64_tr_b16 v[120:121], v187 offset:0x1000
	ds_read_b64_tr_b16 v[122:123], v187 offset:0x1800
	ds_read_b64_tr_b16 v[124:125], v187 offset:0x2000
	ds_read_b64_tr_b16 v[126:127], v187 offset:0x2800
	ds_read_b64_tr_b16 v[128:129], v187 offset:0x3000
	ds_read_b64_tr_b16 v[130:131], v187 offset:0x3800
	s_waitcnt lgkmcnt(0)
	s_nop 0
	v_mfma_f32_32x32x16_bf16 v[0:15], v[100:103], v[116:119], v[0:15]
	ds_read_b64_tr_b16 v[116:117], v187 offset:0x200
	ds_read_b64_tr_b16 v[118:119], v187 offset:0xa00
	v_mfma_f32_32x32x16_bf16 v[0:15], v[104:107], v[120:123], v[0:15]
	ds_read_b64_tr_b16 v[120:121], v187 offset:0x1200
	ds_read_b64_tr_b16 v[122:123], v187 offset:0x1a00
	v_mfma_f32_32x32x16_bf16 v[0:15], v[108:111], v[124:127], v[0:15]
	ds_read_b64_tr_b16 v[124:125], v187 offset:0x2200
	ds_read_b64_tr_b16 v[126:127], v187 offset:0x2a00
	v_mfma_f32_32x32x16_bf16 v[0:15], v[112:115], v[128:131], v[0:15]
	ds_read_b64_tr_b16 v[128:129], v187 offset:0x3200
	ds_read_b64_tr_b16 v[130:131], v187 offset:0x3a00
	s_waitcnt lgkmcnt(0)
	v_mfma_f32_32x32x16_bf16 v[48:63], v[100:103], v[116:119], v[48:63]
	ds_read_b64_tr_b16 v[116:117], v187 offset:0x400
	ds_read_b64_tr_b16 v[118:119], v187 offset:0xc00
	v_mfma_f32_32x32x16_bf16 v[48:63], v[104:107], v[120:123], v[48:63]
	ds_read_b64_tr_b16 v[120:121], v187 offset:0x1400
	ds_read_b64_tr_b16 v[122:123], v187 offset:0x1c00
	v_mfma_f32_32x32x16_bf16 v[48:63], v[108:111], v[124:127], v[48:63]
	ds_read_b64_tr_b16 v[124:125], v187 offset:0x2400
	ds_read_b64_tr_b16 v[126:127], v187 offset:0x2c00
	v_mfma_f32_32x32x16_bf16 v[48:63], v[112:115], v[128:131], v[48:63]
	ds_read_b64_tr_b16 v[128:129], v187 offset:0x3400
	ds_read_b64_tr_b16 v[130:131], v187 offset:0x3c00
	s_waitcnt lgkmcnt(0)
	v_mfma_f32_32x32x16_bf16 v[32:47], v[100:103], v[116:119], v[32:47]
	ds_read_b64_tr_b16 v[116:117], v187 offset:0x600
	ds_read_b64_tr_b16 v[118:119], v187 offset:0xe00
	v_mfma_f32_32x32x16_bf16 v[32:47], v[104:107], v[120:123], v[32:47]
	ds_read_b64_tr_b16 v[120:121], v187 offset:0x1600
	ds_read_b64_tr_b16 v[122:123], v187 offset:0x1e00
	v_mfma_f32_32x32x16_bf16 v[32:47], v[108:111], v[124:127], v[32:47]
	ds_read_b64_tr_b16 v[124:125], v187 offset:0x2600
	ds_read_b64_tr_b16 v[126:127], v187 offset:0x2e00
	v_mfma_f32_32x32x16_bf16 v[32:47], v[112:115], v[128:131], v[32:47]
	ds_read_b64_tr_b16 v[128:129], v187 offset:0x3600
	ds_read_b64_tr_b16 v[130:131], v187 offset:0x3e00
	s_waitcnt lgkmcnt(0)
	v_mfma_f32_32x32x16_bf16 v[16:31], v[100:103], v[116:119], v[16:31]
	v_max_f32_e32 v100, v81, v81
	v_max_f32_e32 v101, v80, v80
	v_max_f32_e32 v100, v101, v100
	v_max3_f32 v100, v100, v82, v83
	v_max3_f32 v100, v100, v84, v85
	v_max3_f32 v100, v100, v86, v87
	v_max3_f32 v100, v100, v88, v89
	v_max3_f32 v100, v100, v90, v91
	v_max3_f32 v100, v100, v92, v93
	v_mfma_f32_32x32x16_bf16 v[16:31], v[104:107], v[120:123], v[16:31]
	v_max3_f32 v100, v100, v94, v95
	v_max3_f32 v100, v100, v64, v65
	v_max3_f32 v100, v100, v66, v67
	v_max3_f32 v100, v100, v68, v69
	v_max3_f32 v100, v100, v70, v71
	v_max3_f32 v100, v100, v72, v73
	v_max3_f32 v100, v100, v74, v75
	v_max3_f32 v100, v100, v76, v77
	v_mfma_f32_32x32x16_bf16 v[16:31], v[108:111], v[124:127], v[16:31]
	v_max3_f32 v100, v100, v78, v79
	v_mov_b32_e32 v101, v100
	s_nop 1
	v_permlane32_swap_b32_e32 v100, v101
	v_max_f32_e32 v101, v101, v101
	v_max_f32_e32 v100, v100, v100
	v_max_f32_e32 v100, v100, v101
	v_sub_f32_e32 v101, v100, v170
	v_cmp_ge_f32_e32 vcc, s92, v101
	v_max_f32_e32 v101, v170, v170
	v_max_f32_e32 v101, v101, v100
	v_mfma_f32_32x32x16_bf16 v[16:31], v[112:115], v[128:131], v[16:31]
	v_sub_f32_e32 v100, v170, v101
	v_mul_f32_e32 v100, 0x3e0293ee, v100
	v_exp_f32_e32 v100, v100
	s_cmp_eq_u64 vcc, exec
	s_cselect_b64 s[42:43], -1, 0
	v_cndmask_b32_e64 v100, v100, 1.0, s[42:43]
	v_cmp_gt_f32_e32 vcc, 1.0, v100
	s_barrier
	s_cbranch_vccz .LBB0_542
	s_and_saveexec_b64 s[6:7], s[40:41]
	ds_write_b32 v184, v100 offset:128
	s_or_b64 exec, exec, s[6:7]
	s_waitcnt lgkmcnt(0)
	ds_read_b128 v[102:105], v182 offset:224
	ds_read_b128 v[106:109], v182 offset:192
	ds_read_b128 v[110:113], v182 offset:160
	ds_read_b128 v[114:117], v182 offset:128
	s_waitcnt lgkmcnt(3)
	v_pk_mul_f32 v[14:15], v[14:15], v[104:105]
	s_waitcnt lgkmcnt(2)
	v_pk_mul_f32 v[10:11], v[10:11], v[108:109]
	s_waitcnt lgkmcnt(1)
	v_pk_mul_f32 v[6:7], v[6:7], v[112:113]
	s_waitcnt lgkmcnt(0)
	v_pk_mul_f32 v[2:3], v[2:3], v[116:117]
	v_pk_mul_f32 v[12:13], v[12:13], v[102:103]
	v_pk_mul_f32 v[8:9], v[8:9], v[106:107]
	v_pk_mul_f32 v[4:5], v[4:5], v[110:111]
	v_pk_mul_f32 v[0:1], v[0:1], v[114:115]
	v_pk_mul_f32 v[62:63], v[62:63], v[104:105]
	v_pk_mul_f32 v[58:59], v[58:59], v[108:109]
	v_pk_mul_f32 v[54:55], v[54:55], v[112:113]
	v_pk_mul_f32 v[50:51], v[50:51], v[116:117]
	v_pk_mul_f32 v[60:61], v[60:61], v[102:103]
	v_pk_mul_f32 v[56:57], v[56:57], v[106:107]
	v_pk_mul_f32 v[52:53], v[52:53], v[110:111]
	v_pk_mul_f32 v[48:49], v[48:49], v[114:115]
	v_pk_mul_f32 v[46:47], v[46:47], v[104:105]
	v_pk_mul_f32 v[42:43], v[42:43], v[108:109]
	v_pk_mul_f32 v[38:39], v[38:39], v[112:113]
	v_pk_mul_f32 v[34:35], v[34:35], v[116:117]
	v_pk_mul_f32 v[44:45], v[44:45], v[102:103]
	v_pk_mul_f32 v[40:41], v[40:41], v[106:107]
	v_pk_mul_f32 v[36:37], v[36:37], v[110:111]
	v_pk_mul_f32 v[32:33], v[32:33], v[114:115]
	v_pk_mul_f32 v[30:31], v[30:31], v[104:105]
	v_pk_mul_f32 v[26:27], v[26:27], v[108:109]
	v_pk_mul_f32 v[22:23], v[22:23], v[112:113]
	v_pk_mul_f32 v[18:19], v[18:19], v[116:117]
	v_pk_mul_f32 v[28:29], v[28:29], v[102:103]
	v_pk_mul_f32 v[24:25], v[24:25], v[106:107]
	v_pk_mul_f32 v[20:21], v[20:21], v[110:111]
	v_pk_mul_f32 v[16:17], v[16:17], v[114:115]
